# vm10 on the K/V GEMM loops of P3 only (counted DMA waits moved next to each reading phase, 10 loads in flight), on reshead
# speedup vs baseline: 1.0047x; 1.0047x over previous
.LBB0_558:
	s_add_u32 s12, s8, s10
	ds_read_b128 v[148:151], v142
	ds_read_b128 v[152:155], v142 offset:1024
	ds_read_b128 v[156:159], v142 offset:2048
	ds_read_b128 v[160:163], v142 offset:3072
	s_addc_u32 s13, s9, s11
	s_add_u32 s12, s12, 0x3000100
	s_addc_u32 s13, s13, 0
	s_add_u32 s40, s26, s10
	s_addc_u32 s41, s27, s11
	s_cmpk_eq_i32 s10, 0xf00
	s_cselect_b32 s15, s3, s13
	s_cselect_b32 s14, s2, s12
	s_cselect_b32 s13, s1, s41
	s_cselect_b32 s12, s0, s40
	s_mov_b32 m0, s29
	v_lshl_add_u64 v[168:169], v[136:137], 0, s[10:11]
	ds_read_b128 v[164:167], v143
	ds_read_b128 v[172:175], v143 offset:1024
	ds_read_b128 v[176:179], v143 offset:2048
	ds_read_b128 v[180:183], v143 offset:3072
	ds_read_b128 v[184:187], v143 offset:4096
	ds_read_b128 v[188:191], v143 offset:5120
	ds_read_b128 v[192:195], v143 offset:6144
	ds_read_b128 v[196:199], v143 offset:7168
	global_load_lds_dwordx4 v[168:169], off
	v_lshl_add_u64 v[168:169], v[138:139], 0, s[10:11]
	s_mov_b32 m0, s30
	s_nop 0
	global_load_lds_dwordx4 v[168:169], off
	s_waitcnt vmcnt(10)
	s_waitcnt lgkmcnt(8)
	s_barrier
	s_waitcnt lgkmcnt(0)
	s_setprio 1
	s_waitcnt lgkmcnt(0)
	v_mfma_f32_16x16x32_bf16 v[124:127], v[148:151], v[164:167], v[124:127]
	v_mfma_f32_16x16x32_bf16 v[120:123], v[156:159], v[164:167], v[120:123]
	v_mfma_f32_16x16x32_bf16 v[116:119], v[148:151], v[176:179], v[116:119]
	v_mfma_f32_16x16x32_bf16 v[112:115], v[156:159], v[176:179], v[112:115]
	v_mfma_f32_16x16x32_bf16 v[100:103], v[148:151], v[184:187], v[100:103]
	v_mfma_f32_16x16x32_bf16 v[96:99], v[156:159], v[184:187], v[96:99]
	v_mfma_f32_16x16x32_bf16 v[84:87], v[148:151], v[192:195], v[84:87]
	v_mfma_f32_16x16x32_bf16 v[80:83], v[156:159], v[192:195], v[80:83]
	v_mfma_f32_16x16x32_bf16 v[124:127], v[152:155], v[172:175], v[124:127]
	v_mfma_f32_16x16x32_bf16 v[120:123], v[160:163], v[172:175], v[120:123]
	v_mfma_f32_16x16x32_bf16 v[116:119], v[152:155], v[180:183], v[116:119]
	v_mfma_f32_16x16x32_bf16 v[112:115], v[160:163], v[180:183], v[112:115]
	v_mfma_f32_16x16x32_bf16 v[100:103], v[152:155], v[188:191], v[100:103]
	v_mfma_f32_16x16x32_bf16 v[96:99], v[160:163], v[188:191], v[96:99]
	v_mfma_f32_16x16x32_bf16 v[84:87], v[152:155], v[196:199], v[84:87]
	v_mfma_f32_16x16x32_bf16 v[80:83], v[160:163], v[196:199], v[80:83]
	s_setprio 0
	s_barrier
	s_mov_b32 m0, s31
	v_lshl_add_u64 v[168:169], s[12:13], 0, v[130:131]
	ds_read_b128 v[200:203], v144
	ds_read_b128 v[204:207], v144 offset:1024
	ds_read_b128 v[208:211], v144 offset:2048
	ds_read_b128 v[212:215], v144 offset:3072
	global_load_lds_dwordx4 v[168:169], off
	v_lshl_add_u64 v[216:217], s[12:13], 0, v[134:135]
	s_mov_b32 m0, s33
	s_nop 0
	global_load_lds_dwordx4 v[216:217], off
	s_waitcnt vmcnt(10)
	s_barrier
	s_waitcnt lgkmcnt(0)
	s_setprio 1
	s_waitcnt lgkmcnt(0)
	v_mfma_f32_16x16x32_bf16 v[108:111], v[200:203], v[164:167], v[108:111]
	v_mfma_f32_16x16x32_bf16 v[104:107], v[208:211], v[164:167], v[104:107]
	v_mfma_f32_16x16x32_bf16 v[92:95], v[200:203], v[176:179], v[92:95]
	v_mfma_f32_16x16x32_bf16 v[88:91], v[208:211], v[176:179], v[88:91]
	v_mfma_f32_16x16x32_bf16 v[76:79], v[200:203], v[184:187], v[76:79]
	v_mfma_f32_16x16x32_bf16 v[72:75], v[208:211], v[184:187], v[72:75]
	v_mfma_f32_16x16x32_bf16 v[68:71], v[200:203], v[192:195], v[68:71]
	v_mfma_f32_16x16x32_bf16 v[64:67], v[208:211], v[192:195], v[64:67]
	v_mfma_f32_16x16x32_bf16 v[108:111], v[204:207], v[172:175], v[108:111]
	v_mfma_f32_16x16x32_bf16 v[104:107], v[212:215], v[172:175], v[104:107]
	v_mfma_f32_16x16x32_bf16 v[92:95], v[204:207], v[180:183], v[92:95]
	v_mfma_f32_16x16x32_bf16 v[88:91], v[212:215], v[180:183], v[88:91]
	v_mfma_f32_16x16x32_bf16 v[76:79], v[204:207], v[188:191], v[76:79]
	v_mfma_f32_16x16x32_bf16 v[72:75], v[212:215], v[188:191], v[72:75]
	v_mfma_f32_16x16x32_bf16 v[68:71], v[204:207], v[196:199], v[68:71]
	v_mfma_f32_16x16x32_bf16 v[64:67], v[212:215], v[196:199], v[64:67]
	s_setprio 0
	s_mov_b32 m0, s19
	v_lshl_add_u64 v[218:219], s[14:15], 0, v[128:129]
	s_barrier
	ds_read_b128 v[164:167], v143 offset:16384
	ds_read_b128 v[172:175], v143 offset:17408
	ds_read_b128 v[176:179], v143 offset:18432
	ds_read_b128 v[180:183], v143 offset:19456
	ds_read_b128 v[184:187], v143 offset:20480
	ds_read_b128 v[188:191], v143 offset:21504
	ds_read_b128 v[192:195], v143 offset:22528
	ds_read_b128 v[196:199], v143 offset:23552
	global_load_lds_dwordx4 v[218:219], off
	v_lshl_add_u64 v[220:221], s[14:15], 0, v[132:133]
	s_mov_b32 m0, s20
	s_nop 0
	global_load_lds_dwordx4 v[220:221], off
	s_barrier
	s_waitcnt lgkmcnt(0)
	s_setprio 1
	s_waitcnt lgkmcnt(0)
	v_mfma_f32_16x16x32_bf16 v[60:63], v[148:151], v[164:167], v[60:63]
	v_mfma_f32_16x16x32_bf16 v[56:59], v[156:159], v[164:167], v[56:59]
	v_mfma_f32_16x16x32_bf16 v[52:55], v[148:151], v[176:179], v[52:55]
	v_mfma_f32_16x16x32_bf16 v[48:51], v[156:159], v[176:179], v[48:51]
	v_mfma_f32_16x16x32_bf16 v[36:39], v[148:151], v[184:187], v[36:39]
	v_mfma_f32_16x16x32_bf16 v[32:35], v[156:159], v[184:187], v[32:35]
	v_mfma_f32_16x16x32_bf16 v[20:23], v[148:151], v[192:195], v[20:23]
	v_mfma_f32_16x16x32_bf16 v[16:19], v[156:159], v[192:195], v[16:19]
	v_mfma_f32_16x16x32_bf16 v[60:63], v[152:155], v[172:175], v[60:63]
	v_mfma_f32_16x16x32_bf16 v[56:59], v[160:163], v[172:175], v[56:59]
	v_mfma_f32_16x16x32_bf16 v[52:55], v[152:155], v[180:183], v[52:55]
	v_mfma_f32_16x16x32_bf16 v[48:51], v[160:163], v[180:183], v[48:51]
	v_mfma_f32_16x16x32_bf16 v[36:39], v[152:155], v[188:191], v[36:39]
	v_mfma_f32_16x16x32_bf16 v[32:35], v[160:163], v[188:191], v[32:35]
	v_mfma_f32_16x16x32_bf16 v[20:23], v[152:155], v[196:199], v[20:23]
	v_mfma_f32_16x16x32_bf16 v[16:19], v[160:163], v[196:199], v[16:19]
	s_setprio 0
	s_barrier
	s_add_u32 s40, s12, 0x80000
	s_addc_u32 s41, s13, 0
	s_mov_b32 m0, s34
	v_lshl_add_u64 v[148:149], s[40:41], 0, v[130:131]
	global_load_lds_dwordx4 v[148:149], off
	v_lshl_add_u64 v[148:149], s[40:41], 0, v[134:135]
	s_mov_b32 m0, s35
	s_nop 0
	global_load_lds_dwordx4 v[148:149], off
	s_waitcnt vmcnt(10)
	s_barrier
	s_setprio 1
	v_mfma_f32_16x16x32_bf16 v[44:47], v[200:203], v[164:167], v[44:47]
	v_mfma_f32_16x16x32_bf16 v[40:43], v[208:211], v[164:167], v[40:43]
	v_mfma_f32_16x16x32_bf16 v[28:31], v[200:203], v[176:179], v[28:31]
	v_mfma_f32_16x16x32_bf16 v[24:27], v[208:211], v[176:179], v[24:27]
	v_mfma_f32_16x16x32_bf16 v[12:15], v[200:203], v[184:187], v[12:15]
	v_mfma_f32_16x16x32_bf16 v[8:11], v[208:211], v[184:187], v[8:11]
	v_mfma_f32_16x16x32_bf16 v[4:7], v[200:203], v[192:195], v[4:7]
	v_mfma_f32_16x16x32_bf16 v[0:3], v[208:211], v[192:195], v[0:3]
	v_mfma_f32_16x16x32_bf16 v[44:47], v[204:207], v[172:175], v[44:47]
	v_mfma_f32_16x16x32_bf16 v[40:43], v[212:215], v[172:175], v[40:43]
	v_mfma_f32_16x16x32_bf16 v[28:31], v[204:207], v[180:183], v[28:31]
	v_mfma_f32_16x16x32_bf16 v[24:27], v[212:215], v[180:183], v[24:27]
	v_mfma_f32_16x16x32_bf16 v[12:15], v[204:207], v[188:191], v[12:15]
	v_mfma_f32_16x16x32_bf16 v[8:11], v[212:215], v[188:191], v[8:11]
	v_mfma_f32_16x16x32_bf16 v[4:7], v[204:207], v[196:199], v[4:7]
	v_mfma_f32_16x16x32_bf16 v[0:3], v[212:215], v[196:199], v[0:3]
	s_setprio 0
	s_barrier
	ds_read_b128 v[148:151], v145
	ds_read_b128 v[152:155], v145 offset:1024
	ds_read_b128 v[156:159], v145 offset:2048
	ds_read_b128 v[160:163], v145 offset:3072
	s_add_u32 s14, s14, 0x80000
	s_addc_u32 s15, s15, 0
	s_mov_b32 m0, s21
	v_lshl_add_u64 v[200:201], s[14:15], 0, v[128:129]
	ds_read_b128 v[164:167], v143 offset:32768
	ds_read_b128 v[172:175], v143 offset:33792
	ds_read_b128 v[176:179], v143 offset:34816
	ds_read_b128 v[180:183], v143 offset:35840
	ds_read_b128 v[184:187], v143 offset:36864
	ds_read_b128 v[188:191], v143 offset:37888
	ds_read_b128 v[192:195], v143 offset:38912
	ds_read_b128 v[196:199], v143 offset:39936
	global_load_lds_dwordx4 v[200:201], off
	v_lshl_add_u64 v[200:201], s[14:15], 0, v[132:133]
	s_mov_b32 m0, s22
	s_nop 0
	global_load_lds_dwordx4 v[200:201], off
	s_waitcnt vmcnt(10)
	s_waitcnt lgkmcnt(8)
	s_barrier
	s_waitcnt lgkmcnt(0)
	s_setprio 1
	s_waitcnt lgkmcnt(0)
	v_mfma_f32_16x16x32_bf16 v[124:127], v[148:151], v[164:167], v[124:127]
	v_mfma_f32_16x16x32_bf16 v[120:123], v[156:159], v[164:167], v[120:123]
	v_mfma_f32_16x16x32_bf16 v[116:119], v[148:151], v[176:179], v[116:119]
	v_mfma_f32_16x16x32_bf16 v[112:115], v[156:159], v[176:179], v[112:115]
	v_mfma_f32_16x16x32_bf16 v[100:103], v[148:151], v[184:187], v[100:103]
	v_mfma_f32_16x16x32_bf16 v[96:99], v[156:159], v[184:187], v[96:99]
	v_mfma_f32_16x16x32_bf16 v[84:87], v[148:151], v[192:195], v[84:87]
	v_mfma_f32_16x16x32_bf16 v[80:83], v[156:159], v[192:195], v[80:83]
	v_mfma_f32_16x16x32_bf16 v[124:127], v[152:155], v[172:175], v[124:127]
	v_mfma_f32_16x16x32_bf16 v[120:123], v[160:163], v[172:175], v[120:123]
	v_mfma_f32_16x16x32_bf16 v[116:119], v[152:155], v[180:183], v[116:119]
	v_mfma_f32_16x16x32_bf16 v[112:115], v[160:163], v[180:183], v[112:115]
	v_mfma_f32_16x16x32_bf16 v[100:103], v[152:155], v[188:191], v[100:103]
	v_mfma_f32_16x16x32_bf16 v[96:99], v[160:163], v[188:191], v[96:99]
	v_mfma_f32_16x16x32_bf16 v[84:87], v[152:155], v[196:199], v[84:87]
	v_mfma_f32_16x16x32_bf16 v[80:83], v[160:163], v[196:199], v[80:83]
	s_setprio 0
	s_barrier
	s_mov_b32 m0, s36
	v_lshl_add_u64 v[168:169], v[168:169], 0, s[6:7]
	ds_read_b128 v[200:203], v146
	ds_read_b128 v[204:207], v146 offset:1024
	ds_read_b128 v[208:211], v146 offset:2048
	ds_read_b128 v[212:215], v146 offset:3072
	global_load_lds_dwordx4 v[168:169], off
	v_lshl_add_u64 v[168:169], v[216:217], 0, s[6:7]
	s_mov_b32 m0, s37
	s_nop 0
	global_load_lds_dwordx4 v[168:169], off
	s_waitcnt vmcnt(10)
	s_barrier
	s_waitcnt lgkmcnt(0)
	s_setprio 1
	s_waitcnt lgkmcnt(0)
	v_mfma_f32_16x16x32_bf16 v[108:111], v[200:203], v[164:167], v[108:111]
	v_mfma_f32_16x16x32_bf16 v[104:107], v[208:211], v[164:167], v[104:107]
	v_mfma_f32_16x16x32_bf16 v[92:95], v[200:203], v[176:179], v[92:95]
	v_mfma_f32_16x16x32_bf16 v[88:91], v[208:211], v[176:179], v[88:91]
	v_mfma_f32_16x16x32_bf16 v[76:79], v[200:203], v[184:187], v[76:79]
	v_mfma_f32_16x16x32_bf16 v[72:75], v[208:211], v[184:187], v[72:75]
	v_mfma_f32_16x16x32_bf16 v[68:71], v[200:203], v[192:195], v[68:71]
	v_mfma_f32_16x16x32_bf16 v[64:67], v[208:211], v[192:195], v[64:67]
	v_mfma_f32_16x16x32_bf16 v[108:111], v[204:207], v[172:175], v[108:111]
	v_mfma_f32_16x16x32_bf16 v[104:107], v[212:215], v[172:175], v[104:107]
	v_mfma_f32_16x16x32_bf16 v[92:95], v[204:207], v[180:183], v[92:95]
	v_mfma_f32_16x16x32_bf16 v[88:91], v[212:215], v[180:183], v[88:91]
	v_mfma_f32_16x16x32_bf16 v[76:79], v[204:207], v[188:191], v[76:79]
	v_mfma_f32_16x16x32_bf16 v[72:75], v[212:215], v[188:191], v[72:75]
	v_mfma_f32_16x16x32_bf16 v[68:71], v[204:207], v[196:199], v[68:71]
	v_mfma_f32_16x16x32_bf16 v[64:67], v[212:215], v[196:199], v[64:67]
	s_setprio 0
	s_mov_b32 m0, s24
	v_lshl_add_u64 v[168:169], v[218:219], 0, s[6:7]
	s_barrier
	ds_read_b128 v[164:167], v143 offset:49152
	ds_read_b128 v[172:175], v143 offset:50176
	ds_read_b128 v[176:179], v143 offset:51200
	ds_read_b128 v[180:183], v143 offset:52224
	ds_read_b128 v[184:187], v143 offset:53248
	ds_read_b128 v[188:191], v143 offset:54272
	ds_read_b128 v[192:195], v143 offset:55296
	ds_read_b128 v[196:199], v143 offset:56320
	global_load_lds_dwordx4 v[168:169], off
	v_lshl_add_u64 v[168:169], v[220:221], 0, s[6:7]
	s_mov_b32 m0, s25
	s_nop 0
	global_load_lds_dwordx4 v[168:169], off
	s_barrier
	s_waitcnt lgkmcnt(0)
	s_setprio 1
	s_waitcnt lgkmcnt(0)
	v_mfma_f32_16x16x32_bf16 v[60:63], v[148:151], v[164:167], v[60:63]
	v_mfma_f32_16x16x32_bf16 v[56:59], v[156:159], v[164:167], v[56:59]
	v_mfma_f32_16x16x32_bf16 v[52:55], v[148:151], v[176:179], v[52:55]
	v_mfma_f32_16x16x32_bf16 v[48:51], v[156:159], v[176:179], v[48:51]
	v_mfma_f32_16x16x32_bf16 v[36:39], v[148:151], v[184:187], v[36:39]
	v_mfma_f32_16x16x32_bf16 v[32:35], v[156:159], v[184:187], v[32:35]
	v_mfma_f32_16x16x32_bf16 v[20:23], v[148:151], v[192:195], v[20:23]
	v_mfma_f32_16x16x32_bf16 v[16:19], v[156:159], v[192:195], v[16:19]
	v_mfma_f32_16x16x32_bf16 v[60:63], v[152:155], v[172:175], v[60:63]
	v_mfma_f32_16x16x32_bf16 v[56:59], v[160:163], v[172:175], v[56:59]
	v_mfma_f32_16x16x32_bf16 v[52:55], v[152:155], v[180:183], v[52:55]
	v_mfma_f32_16x16x32_bf16 v[48:51], v[160:163], v[180:183], v[48:51]
	v_mfma_f32_16x16x32_bf16 v[36:39], v[152:155], v[188:191], v[36:39]
	v_mfma_f32_16x16x32_bf16 v[32:35], v[160:163], v[188:191], v[32:35]
	v_mfma_f32_16x16x32_bf16 v[20:23], v[152:155], v[196:199], v[20:23]
	v_mfma_f32_16x16x32_bf16 v[16:19], v[160:163], v[196:199], v[16:19]
	s_setprio 0
	s_barrier
	s_add_u32 s12, s12, 0x80080
	s_addc_u32 s13, s13, 0
	s_mov_b32 m0, s38
	v_lshl_add_u64 v[148:149], s[12:13], 0, v[130:131]
	global_load_lds_dwordx4 v[148:149], off
	v_lshl_add_u64 v[148:149], s[12:13], 0, v[134:135]
	s_mov_b32 m0, s39
	s_nop 0
	global_load_lds_dwordx4 v[148:149], off
	s_waitcnt vmcnt(10)
	s_barrier
	s_setprio 1
	v_mfma_f32_16x16x32_bf16 v[44:47], v[200:203], v[164:167], v[44:47]
	v_mfma_f32_16x16x32_bf16 v[40:43], v[208:211], v[164:167], v[40:43]
	v_mfma_f32_16x16x32_bf16 v[28:31], v[200:203], v[176:179], v[28:31]
	v_mfma_f32_16x16x32_bf16 v[24:27], v[208:211], v[176:179], v[24:27]
	v_mfma_f32_16x16x32_bf16 v[12:15], v[200:203], v[184:187], v[12:15]
	v_mfma_f32_16x16x32_bf16 v[8:11], v[208:211], v[184:187], v[8:11]
	v_mfma_f32_16x16x32_bf16 v[4:7], v[200:203], v[192:195], v[4:7]
	v_mfma_f32_16x16x32_bf16 v[0:3], v[208:211], v[192:195], v[0:3]
	v_mfma_f32_16x16x32_bf16 v[44:47], v[204:207], v[172:175], v[44:47]
	v_mfma_f32_16x16x32_bf16 v[40:43], v[212:215], v[172:175], v[40:43]
	v_mfma_f32_16x16x32_bf16 v[28:31], v[204:207], v[180:183], v[28:31]
	v_mfma_f32_16x16x32_bf16 v[24:27], v[212:215], v[180:183], v[24:27]
	v_mfma_f32_16x16x32_bf16 v[12:15], v[204:207], v[188:191], v[12:15]
	v_mfma_f32_16x16x32_bf16 v[8:11], v[212:215], v[188:191], v[8:11]
	v_mfma_f32_16x16x32_bf16 v[4:7], v[204:207], v[196:199], v[4:7]
	v_mfma_f32_16x16x32_bf16 v[0:3], v[212:215], v[196:199], v[0:3]
	s_setprio 0
	s_add_i32 s28, s28, 2
	s_add_u32 s10, s10, 0x100
	s_addc_u32 s11, s11, 0
	s_cmp_gt_u32 s28, 29
	s_barrier
	s_cbranch_scc0 .LBB0_558
	s_add_u32 s0, s66, 0x8c00000
	s_addc_u32 s1, s67, 0
	s_and_b32 s2, 0xffff, s18
	v_lshl_or_b32 v129, s2, 8, v140
	v_lshl_add_u32 v128, s17, 8, v141
	v_or_b32_e32 v132, s23, v129
	v_mov_b32_e32 v129, 0
	v_cvt_pk_bf16_f32 v68, v68, v69
	v_cvt_pk_bf16_f32 v69, v70, v71
	v_cvt_pk_bf16_f32 v70, v64, v65
	v_add_u32_e32 v64, 0x80, v128
	v_mov_b32_e32 v65, v129
	v_lshlrev_b64 v[130:131], 11, v[128:129]
	v_cvt_pk_bf16_f32 v108, v108, v109
	v_cvt_pk_bf16_f32 v109, v110, v111
	v_cvt_pk_bf16_f32 v110, v104, v105
	v_or_b32_e32 v104, 16, v128
	v_mov_b32_e32 v105, v129
	v_lshlrev_b64 v[64:65], 11, v[64:65]
	v_cvt_pk_bf16_f32 v44, v44, v45
	v_cvt_pk_bf16_f32 v45, v46, v47
	v_cvt_pk_bf16_f32 v46, v40, v41
	v_add_u32_e32 v40, 0x90, v128
	v_mov_b32_e32 v41, v129
	v_lshl_add_u64 v[130:131], s[0:1], 0, v[130:131]
	v_lshlrev_b32_e32 v132, 1, v132
	v_mov_b32_e32 v133, v129
	v_lshlrev_b64 v[104:105], 11, v[104:105]
	v_cvt_pk_bf16_f32 v92, v92, v93
	v_cvt_pk_bf16_f32 v93, v94, v95
	v_cvt_pk_bf16_f32 v94, v88, v89
	v_or_b32_e32 v88, 32, v128
	v_mov_b32_e32 v89, v129
	v_lshl_add_u64 v[64:65], s[0:1], 0, v[64:65]
	v_lshlrev_b64 v[40:41], 11, v[40:41]
	v_cvt_pk_bf16_f32 v28, v28, v29
	v_cvt_pk_bf16_f32 v29, v30, v31
	v_cvt_pk_bf16_f32 v30, v24, v25
	v_add_u32_e32 v24, 0xa0, v128
	v_mov_b32_e32 v25, v129
	v_lshl_add_u64 v[130:131], v[130:131], 0, v[132:133]
	v_cvt_pk_bf16_f32 v111, v106, v107
	v_lshl_add_u64 v[104:105], s[0:1], 0, v[104:105]
	v_lshlrev_b64 v[88:89], 11, v[88:89]
	v_cvt_pk_bf16_f32 v76, v76, v77
	v_cvt_pk_bf16_f32 v77, v78, v79
	v_cvt_pk_bf16_f32 v78, v72, v73
	v_or_b32_e32 v72, 48, v128
	v_mov_b32_e32 v73, v129
	v_lshl_add_u64 v[64:65], v[64:65], 0, v[132:133]
	v_cvt_pk_bf16_f32 v47, v42, v43
	v_lshl_add_u64 v[40:41], s[0:1], 0, v[40:41]
	v_lshlrev_b64 v[24:25], 11, v[24:25]
	v_add_u32_e32 v128, 0xb0, v128
	global_store_dwordx4 v[130:131], v[108:111], off offset:256
	v_cvt_pk_bf16_f32 v95, v90, v91
	v_lshl_add_u64 v[88:89], s[0:1], 0, v[88:89]
	v_lshl_add_u64 v[108:109], v[104:105], 0, v[132:133]
	v_lshlrev_b64 v[72:73], 11, v[72:73]
	global_store_dwordx4 v[64:65], v[44:47], off offset:256
	v_cvt_pk_bf16_f32 v31, v26, v27
	v_lshl_add_u64 v[24:25], s[0:1], 0, v[24:25]
	v_lshl_add_u64 v[44:45], v[40:41], 0, v[132:133]
	v_cvt_pk_bf16_f32 v12, v12, v13
	v_cvt_pk_bf16_f32 v13, v14, v15
	v_cvt_pk_bf16_f32 v14, v8, v9
	v_lshlrev_b64 v[8:9], 11, v[128:129]
	global_store_dwordx4 v[108:109], v[92:95], off offset:256
	v_cvt_pk_bf16_f32 v79, v74, v75
	v_lshl_add_u64 v[72:73], s[0:1], 0, v[72:73]
	v_lshl_add_u64 v[92:93], v[88:89], 0, v[132:133]
	global_store_dwordx4 v[44:45], v[28:31], off offset:256
	v_cvt_pk_bf16_f32 v15, v10, v11
	v_lshl_add_u64 v[8:9], s[0:1], 0, v[8:9]
	v_lshl_add_u64 v[28:29], v[24:25], 0, v[132:133]
	v_cvt_pk_bf16_f32 v124, v124, v125
	v_cvt_pk_bf16_f32 v125, v126, v127
	v_cvt_pk_bf16_f32 v126, v120, v121
	v_cvt_pk_bf16_f32 v127, v122, v123
	v_cvt_pk_bf16_f32 v104, v116, v117
	v_cvt_pk_bf16_f32 v105, v118, v119
	v_cvt_pk_bf16_f32 v106, v112, v113
	v_cvt_pk_bf16_f32 v107, v114, v115
	v_cvt_pk_bf16_f32 v88, v100, v101
	v_cvt_pk_bf16_f32 v89, v102, v103
	v_cvt_pk_bf16_f32 v90, v96, v97
	v_cvt_pk_bf16_f32 v91, v98, v99
	global_store_dwordx4 v[92:93], v[76:79], off offset:256
	v_cvt_pk_bf16_f32 v74, v80, v81
	v_cvt_pk_bf16_f32 v75, v82, v83
	v_lshl_add_u64 v[76:77], v[72:73], 0, v[132:133]
	v_cvt_pk_bf16_f32 v72, v84, v85
	v_cvt_pk_bf16_f32 v73, v86, v87
	v_cvt_pk_bf16_f32 v71, v66, v67
	v_cvt_pk_bf16_f32 v60, v60, v61
	v_cvt_pk_bf16_f32 v61, v62, v63
	v_cvt_pk_bf16_f32 v62, v56, v57
	v_cvt_pk_bf16_f32 v63, v58, v59
	v_cvt_pk_bf16_f32 v40, v52, v53
	v_cvt_pk_bf16_f32 v41, v54, v55
	v_cvt_pk_bf16_f32 v42, v48, v49
	v_cvt_pk_bf16_f32 v43, v50, v51
	v_cvt_pk_bf16_f32 v24, v36, v37
	v_cvt_pk_bf16_f32 v25, v38, v39
	v_cvt_pk_bf16_f32 v26, v32, v33
	v_cvt_pk_bf16_f32 v27, v34, v35
	global_store_dwordx4 v[28:29], v[12:15], off offset:256
	v_cvt_pk_bf16_f32 v10, v16, v17
	v_cvt_pk_bf16_f32 v11, v18, v19
	v_lshl_add_u64 v[12:13], v[8:9], 0, v[132:133]
	v_cvt_pk_bf16_f32 v8, v20, v21
	v_cvt_pk_bf16_f32 v9, v22, v23
	v_cvt_pk_bf16_f32 v4, v4, v5
	v_cvt_pk_bf16_f32 v5, v6, v7
	v_cvt_pk_bf16_f32 v6, v0, v1
	v_cvt_pk_bf16_f32 v7, v2, v3
	global_store_dwordx4 v[130:131], v[124:127], off
	global_store_dwordx4 v[108:109], v[104:107], off
	global_store_dwordx4 v[92:93], v[88:91], off
	global_store_dwordx4 v[76:77], v[72:75], off
	global_store_dwordx4 v[76:77], v[68:71], off offset:256
	global_store_dwordx4 v[64:65], v[60:63], off
	global_store_dwordx4 v[44:45], v[40:43], off
	global_store_dwordx4 v[28:29], v[24:27], off
	global_store_dwordx4 v[12:13], v[8:11], off
	global_store_dwordx4 v[12:13], v[4:7], off offset:256
	s_waitcnt vmcnt(0)
	s_cmpk_lt_u32 s16, 0x100
	s_cbranch_scc0 .LBB0_561
	s_barrier

.LBB0_578:
	ds_read_b128 v[146:149], v143
	ds_read_b128 v[150:153], v143 offset:1024
	ds_read_b128 v[154:157], v143 offset:2048
	ds_read_b128 v[158:161], v143 offset:3072
	s_add_u32 s22, s20, 0xfff80080
	s_addc_u32 s23, s21, -1
	s_cmp_eq_u32 s46, 28
	s_cselect_b32 s25, s13, s23
	s_cselect_b32 s24, s42, s22
	s_cselect_b32 s23, s15, s45
	s_cselect_b32 s22, s43, s44
	v_lshl_add_u64 v[196:197], s[20:21], 0, v[136:137]
	s_add_i32 m0, s11, 0xc000
	ds_read_b128 v[162:165], v144
	ds_read_b128 v[166:169], v144 offset:1024
	ds_read_b128 v[172:175], v144 offset:2048
	ds_read_b128 v[176:179], v144 offset:3072
	ds_read_b128 v[180:183], v144 offset:4096
	ds_read_b128 v[184:187], v144 offset:5120
	ds_read_b128 v[188:191], v144 offset:6144
	ds_read_b128 v[192:195], v144 offset:7168
	global_load_lds_dwordx4 v[196:197], off
	v_lshl_add_u64 v[196:197], s[20:21], 0, v[138:139]
	s_add_i32 m0, s11, 0xe000
	s_nop 0
	global_load_lds_dwordx4 v[196:197], off
	s_waitcnt vmcnt(10)
	s_waitcnt lgkmcnt(8)
	s_barrier
	s_waitcnt lgkmcnt(0)
	s_setprio 1
	s_waitcnt lgkmcnt(0)
	v_mfma_f32_16x16x32_bf16 v[124:127], v[146:149], v[162:165], v[124:127]
	v_mfma_f32_16x16x32_bf16 v[120:123], v[154:157], v[162:165], v[120:123]
	v_mfma_f32_16x16x32_bf16 v[116:119], v[146:149], v[172:175], v[116:119]
	v_mfma_f32_16x16x32_bf16 v[112:115], v[154:157], v[172:175], v[112:115]
	v_mfma_f32_16x16x32_bf16 v[100:103], v[146:149], v[180:183], v[100:103]
	v_mfma_f32_16x16x32_bf16 v[96:99], v[154:157], v[180:183], v[96:99]
	v_mfma_f32_16x16x32_bf16 v[84:87], v[146:149], v[188:191], v[84:87]
	v_mfma_f32_16x16x32_bf16 v[80:83], v[154:157], v[188:191], v[80:83]
	v_mfma_f32_16x16x32_bf16 v[124:127], v[150:153], v[166:169], v[124:127]
	v_mfma_f32_16x16x32_bf16 v[120:123], v[158:161], v[166:169], v[120:123]
	v_mfma_f32_16x16x32_bf16 v[116:119], v[150:153], v[176:179], v[116:119]
	v_mfma_f32_16x16x32_bf16 v[112:115], v[158:161], v[176:179], v[112:115]
	v_mfma_f32_16x16x32_bf16 v[100:103], v[150:153], v[184:187], v[100:103]
	v_mfma_f32_16x16x32_bf16 v[96:99], v[158:161], v[184:187], v[96:99]
	v_mfma_f32_16x16x32_bf16 v[84:87], v[150:153], v[192:195], v[84:87]
	v_mfma_f32_16x16x32_bf16 v[80:83], v[158:161], v[192:195], v[80:83]
	s_setprio 0
	s_barrier
	s_add_i32 s47, s39, s33
	v_lshl_add_u64 v[212:213], s[22:23], 0, v[130:131]
	s_mov_b32 m0, s47
	ds_read_b128 v[196:199], v145
	ds_read_b128 v[200:203], v145 offset:1024
	ds_read_b128 v[204:207], v145 offset:2048
	ds_read_b128 v[208:211], v145 offset:3072
	global_load_lds_dwordx4 v[212:213], off
	v_lshl_add_u64 v[214:215], s[22:23], 0, v[134:135]
	s_add_i32 m0, s47, 0x2000
	s_nop 0
	global_load_lds_dwordx4 v[214:215], off
	s_waitcnt vmcnt(10)
	s_barrier
	s_waitcnt lgkmcnt(0)
	s_setprio 1
	s_waitcnt lgkmcnt(0)
	v_mfma_f32_16x16x32_bf16 v[108:111], v[196:199], v[162:165], v[108:111]
	v_mfma_f32_16x16x32_bf16 v[104:107], v[204:207], v[162:165], v[104:107]
	v_mfma_f32_16x16x32_bf16 v[92:95], v[196:199], v[172:175], v[92:95]
	v_mfma_f32_16x16x32_bf16 v[88:91], v[204:207], v[172:175], v[88:91]
	v_mfma_f32_16x16x32_bf16 v[76:79], v[196:199], v[180:183], v[76:79]
	v_mfma_f32_16x16x32_bf16 v[72:75], v[204:207], v[180:183], v[72:75]
	v_mfma_f32_16x16x32_bf16 v[68:71], v[196:199], v[188:191], v[68:71]
	v_mfma_f32_16x16x32_bf16 v[64:67], v[204:207], v[188:191], v[64:67]
	v_mfma_f32_16x16x32_bf16 v[108:111], v[200:203], v[166:169], v[108:111]
	v_mfma_f32_16x16x32_bf16 v[104:107], v[208:211], v[166:169], v[104:107]
	v_mfma_f32_16x16x32_bf16 v[92:95], v[200:203], v[176:179], v[92:95]
	v_mfma_f32_16x16x32_bf16 v[88:91], v[208:211], v[176:179], v[88:91]
	v_mfma_f32_16x16x32_bf16 v[76:79], v[200:203], v[184:187], v[76:79]
	v_mfma_f32_16x16x32_bf16 v[72:75], v[208:211], v[184:187], v[72:75]
	v_mfma_f32_16x16x32_bf16 v[68:71], v[200:203], v[192:195], v[68:71]
	v_mfma_f32_16x16x32_bf16 v[64:67], v[208:211], v[192:195], v[64:67]
	s_setprio 0
	s_mov_b32 m0, s11
	v_lshl_add_u64 v[216:217], s[24:25], 0, v[128:129]
	s_barrier
	ds_read_b128 v[162:165], v144 offset:16384
	ds_read_b128 v[166:169], v144 offset:17408
	ds_read_b128 v[172:175], v144 offset:18432
	ds_read_b128 v[176:179], v144 offset:19456
	ds_read_b128 v[180:183], v144 offset:20480
	ds_read_b128 v[184:187], v144 offset:21504
	ds_read_b128 v[188:191], v144 offset:22528
	ds_read_b128 v[192:195], v144 offset:23552
	global_load_lds_dwordx4 v[216:217], off
	v_lshl_add_u64 v[218:219], s[24:25], 0, v[132:133]
	s_mov_b32 m0, s34
	s_nop 0
	global_load_lds_dwordx4 v[218:219], off
	s_barrier
	s_waitcnt lgkmcnt(0)
	s_setprio 1
	s_waitcnt lgkmcnt(0)
	v_mfma_f32_16x16x32_bf16 v[60:63], v[146:149], v[162:165], v[60:63]
	v_mfma_f32_16x16x32_bf16 v[56:59], v[154:157], v[162:165], v[56:59]
	v_mfma_f32_16x16x32_bf16 v[52:55], v[146:149], v[172:175], v[52:55]
	v_mfma_f32_16x16x32_bf16 v[48:51], v[154:157], v[172:175], v[48:51]
	v_mfma_f32_16x16x32_bf16 v[36:39], v[146:149], v[180:183], v[36:39]
	v_mfma_f32_16x16x32_bf16 v[32:35], v[154:157], v[180:183], v[32:35]
	v_mfma_f32_16x16x32_bf16 v[20:23], v[146:149], v[188:191], v[20:23]
	v_mfma_f32_16x16x32_bf16 v[16:19], v[154:157], v[188:191], v[16:19]
	v_mfma_f32_16x16x32_bf16 v[60:63], v[150:153], v[166:169], v[60:63]
	v_mfma_f32_16x16x32_bf16 v[56:59], v[158:161], v[166:169], v[56:59]
	v_mfma_f32_16x16x32_bf16 v[52:55], v[150:153], v[176:179], v[52:55]
	v_mfma_f32_16x16x32_bf16 v[48:51], v[158:161], v[176:179], v[48:51]
	v_mfma_f32_16x16x32_bf16 v[36:39], v[150:153], v[184:187], v[36:39]
	v_mfma_f32_16x16x32_bf16 v[32:35], v[158:161], v[184:187], v[32:35]
	v_mfma_f32_16x16x32_bf16 v[20:23], v[150:153], v[192:195], v[20:23]
	v_mfma_f32_16x16x32_bf16 v[16:19], v[158:161], v[192:195], v[16:19]
	s_setprio 0
	s_barrier
	s_add_u32 s48, s22, 0x80000
	s_addc_u32 s49, s23, 0
	s_add_i32 s47, s40, s33
	v_lshl_add_u64 v[146:147], s[48:49], 0, v[130:131]
	s_mov_b32 m0, s47
	s_nop 0
	global_load_lds_dwordx4 v[146:147], off
	v_lshl_add_u64 v[146:147], s[48:49], 0, v[134:135]
	s_add_i32 m0, s47, 0x2000
	s_nop 0
	global_load_lds_dwordx4 v[146:147], off
	s_waitcnt vmcnt(10)
	s_barrier
	s_setprio 1
	v_mfma_f32_16x16x32_bf16 v[44:47], v[196:199], v[162:165], v[44:47]
	v_mfma_f32_16x16x32_bf16 v[40:43], v[204:207], v[162:165], v[40:43]
	v_mfma_f32_16x16x32_bf16 v[28:31], v[196:199], v[172:175], v[28:31]
	v_mfma_f32_16x16x32_bf16 v[24:27], v[204:207], v[172:175], v[24:27]
	v_mfma_f32_16x16x32_bf16 v[12:15], v[196:199], v[180:183], v[12:15]
	v_mfma_f32_16x16x32_bf16 v[8:11], v[204:207], v[180:183], v[8:11]
	v_mfma_f32_16x16x32_bf16 v[4:7], v[196:199], v[188:191], v[4:7]
	v_mfma_f32_16x16x32_bf16 v[0:3], v[204:207], v[188:191], v[0:3]
	v_mfma_f32_16x16x32_bf16 v[44:47], v[200:203], v[166:169], v[44:47]
	v_mfma_f32_16x16x32_bf16 v[40:43], v[208:211], v[166:169], v[40:43]
	v_mfma_f32_16x16x32_bf16 v[28:31], v[200:203], v[176:179], v[28:31]
	v_mfma_f32_16x16x32_bf16 v[24:27], v[208:211], v[176:179], v[24:27]
	v_mfma_f32_16x16x32_bf16 v[12:15], v[200:203], v[184:187], v[12:15]
	v_mfma_f32_16x16x32_bf16 v[8:11], v[208:211], v[184:187], v[8:11]
	v_mfma_f32_16x16x32_bf16 v[4:7], v[200:203], v[192:195], v[4:7]
	v_mfma_f32_16x16x32_bf16 v[0:3], v[208:211], v[192:195], v[0:3]
	s_setprio 0
	s_add_i32 s47, 0, 0x18000
	v_add_u32_e32 v158, s47, v141
	s_barrier
	ds_read_b128 v[146:149], v158
	ds_read_b128 v[150:153], v158 offset:1024
	ds_read_b128 v[154:157], v158 offset:2048
	ds_read_b128 v[158:161], v158 offset:3072
	s_add_u32 s24, s24, 0x80000
	s_addc_u32 s25, s25, 0
	s_mov_b32 m0, s35
	v_lshl_add_u64 v[196:197], s[24:25], 0, v[128:129]
	ds_read_b128 v[162:165], v144 offset:32768
	ds_read_b128 v[166:169], v144 offset:33792
	ds_read_b128 v[172:175], v144 offset:34816
	ds_read_b128 v[176:179], v144 offset:35840
	ds_read_b128 v[180:183], v144 offset:36864
	ds_read_b128 v[184:187], v144 offset:37888
	ds_read_b128 v[188:191], v144 offset:38912
	ds_read_b128 v[192:195], v144 offset:39936
	global_load_lds_dwordx4 v[196:197], off
	v_lshl_add_u64 v[196:197], s[24:25], 0, v[132:133]
	s_mov_b32 m0, s36
	s_nop 0
	global_load_lds_dwordx4 v[196:197], off
	s_waitcnt vmcnt(10)
	s_waitcnt lgkmcnt(8)
	s_barrier
	s_waitcnt lgkmcnt(0)
	s_setprio 1
	s_waitcnt lgkmcnt(0)
	v_mfma_f32_16x16x32_bf16 v[124:127], v[146:149], v[162:165], v[124:127]
	v_mfma_f32_16x16x32_bf16 v[120:123], v[154:157], v[162:165], v[120:123]
	v_mfma_f32_16x16x32_bf16 v[116:119], v[146:149], v[172:175], v[116:119]
	v_mfma_f32_16x16x32_bf16 v[112:115], v[154:157], v[172:175], v[112:115]
	v_mfma_f32_16x16x32_bf16 v[100:103], v[146:149], v[180:183], v[100:103]
	v_mfma_f32_16x16x32_bf16 v[96:99], v[154:157], v[180:183], v[96:99]
	v_mfma_f32_16x16x32_bf16 v[84:87], v[146:149], v[188:191], v[84:87]
	v_mfma_f32_16x16x32_bf16 v[80:83], v[154:157], v[188:191], v[80:83]
	v_mfma_f32_16x16x32_bf16 v[124:127], v[150:153], v[166:169], v[124:127]
	v_mfma_f32_16x16x32_bf16 v[120:123], v[158:161], v[166:169], v[120:123]
	v_mfma_f32_16x16x32_bf16 v[116:119], v[150:153], v[176:179], v[116:119]
	v_mfma_f32_16x16x32_bf16 v[112:115], v[158:161], v[176:179], v[112:115]
	v_mfma_f32_16x16x32_bf16 v[100:103], v[150:153], v[184:187], v[100:103]
	v_mfma_f32_16x16x32_bf16 v[96:99], v[158:161], v[184:187], v[96:99]
	v_mfma_f32_16x16x32_bf16 v[84:87], v[150:153], v[192:195], v[84:87]
	v_mfma_f32_16x16x32_bf16 v[80:83], v[158:161], v[192:195], v[80:83]
	s_setprio 0
	s_barrier
	s_add_i32 s24, 0, 0x1c000
	s_add_i32 s25, s47, s33
	v_add_u32_e32 v208, s24, v141
	v_lshl_add_u64 v[212:213], v[212:213], 0, s[6:7]
	s_mov_b32 m0, s25
	ds_read_b128 v[196:199], v208
	ds_read_b128 v[200:203], v208 offset:1024
	ds_read_b128 v[204:207], v208 offset:2048
	ds_read_b128 v[208:211], v208 offset:3072
	global_load_lds_dwordx4 v[212:213], off
	v_lshl_add_u64 v[212:213], v[214:215], 0, s[6:7]
	s_add_i32 m0, s25, 0x2000
	s_nop 0
	global_load_lds_dwordx4 v[212:213], off
	s_waitcnt vmcnt(10)
	s_barrier
	s_waitcnt lgkmcnt(0)
	s_setprio 1
	s_waitcnt lgkmcnt(0)
	v_mfma_f32_16x16x32_bf16 v[108:111], v[196:199], v[162:165], v[108:111]
	v_mfma_f32_16x16x32_bf16 v[104:107], v[204:207], v[162:165], v[104:107]
	v_mfma_f32_16x16x32_bf16 v[92:95], v[196:199], v[172:175], v[92:95]
	v_mfma_f32_16x16x32_bf16 v[88:91], v[204:207], v[172:175], v[88:91]
	v_mfma_f32_16x16x32_bf16 v[76:79], v[196:199], v[180:183], v[76:79]
	v_mfma_f32_16x16x32_bf16 v[72:75], v[204:207], v[180:183], v[72:75]
	v_mfma_f32_16x16x32_bf16 v[68:71], v[196:199], v[188:191], v[68:71]
	v_mfma_f32_16x16x32_bf16 v[64:67], v[204:207], v[188:191], v[64:67]
	v_mfma_f32_16x16x32_bf16 v[108:111], v[200:203], v[166:169], v[108:111]
	v_mfma_f32_16x16x32_bf16 v[104:107], v[208:211], v[166:169], v[104:107]
	v_mfma_f32_16x16x32_bf16 v[92:95], v[200:203], v[176:179], v[92:95]
	v_mfma_f32_16x16x32_bf16 v[88:91], v[208:211], v[176:179], v[88:91]
	v_mfma_f32_16x16x32_bf16 v[76:79], v[200:203], v[184:187], v[76:79]
	v_mfma_f32_16x16x32_bf16 v[72:75], v[208:211], v[184:187], v[72:75]
	v_mfma_f32_16x16x32_bf16 v[68:71], v[200:203], v[192:195], v[68:71]
	v_mfma_f32_16x16x32_bf16 v[64:67], v[208:211], v[192:195], v[64:67]
	s_setprio 0
	s_mov_b32 m0, s37
	v_lshl_add_u64 v[212:213], v[216:217], 0, s[6:7]
	s_barrier
	ds_read_b128 v[162:165], v144 offset:49152
	ds_read_b128 v[166:169], v144 offset:50176
	ds_read_b128 v[172:175], v144 offset:51200
	ds_read_b128 v[176:179], v144 offset:52224
	ds_read_b128 v[180:183], v144 offset:53248
	ds_read_b128 v[184:187], v144 offset:54272
	ds_read_b128 v[188:191], v144 offset:55296
	ds_read_b128 v[192:195], v144 offset:56320
	global_load_lds_dwordx4 v[212:213], off
	v_lshl_add_u64 v[212:213], v[218:219], 0, s[6:7]
	s_mov_b32 m0, s38
	s_nop 0
	global_load_lds_dwordx4 v[212:213], off
	s_barrier
	s_waitcnt lgkmcnt(0)
	s_setprio 1
	s_waitcnt lgkmcnt(0)
	v_mfma_f32_16x16x32_bf16 v[60:63], v[146:149], v[162:165], v[60:63]
	v_mfma_f32_16x16x32_bf16 v[56:59], v[154:157], v[162:165], v[56:59]
	v_mfma_f32_16x16x32_bf16 v[52:55], v[146:149], v[172:175], v[52:55]
	v_mfma_f32_16x16x32_bf16 v[48:51], v[154:157], v[172:175], v[48:51]
	v_mfma_f32_16x16x32_bf16 v[36:39], v[146:149], v[180:183], v[36:39]
	v_mfma_f32_16x16x32_bf16 v[32:35], v[154:157], v[180:183], v[32:35]
	v_mfma_f32_16x16x32_bf16 v[20:23], v[146:149], v[188:191], v[20:23]
	v_mfma_f32_16x16x32_bf16 v[16:19], v[154:157], v[188:191], v[16:19]
	v_mfma_f32_16x16x32_bf16 v[60:63], v[150:153], v[166:169], v[60:63]
	v_mfma_f32_16x16x32_bf16 v[56:59], v[158:161], v[166:169], v[56:59]
	v_mfma_f32_16x16x32_bf16 v[52:55], v[150:153], v[176:179], v[52:55]
	v_mfma_f32_16x16x32_bf16 v[48:51], v[158:161], v[176:179], v[48:51]
	v_mfma_f32_16x16x32_bf16 v[36:39], v[150:153], v[184:187], v[36:39]
	v_mfma_f32_16x16x32_bf16 v[32:35], v[158:161], v[184:187], v[32:35]
	v_mfma_f32_16x16x32_bf16 v[20:23], v[150:153], v[192:195], v[20:23]
	v_mfma_f32_16x16x32_bf16 v[16:19], v[158:161], v[192:195], v[16:19]
	s_setprio 0
	s_barrier
	s_add_u32 s22, s22, 0x80080
	s_addc_u32 s23, s23, 0
	s_add_i32 s24, s24, s33
	v_lshl_add_u64 v[146:147], s[22:23], 0, v[130:131]
	s_mov_b32 m0, s24
	s_nop 0
	global_load_lds_dwordx4 v[146:147], off
	v_lshl_add_u64 v[146:147], s[22:23], 0, v[134:135]
	s_add_i32 m0, s24, 0x2000
	s_nop 0
	global_load_lds_dwordx4 v[146:147], off
	s_waitcnt vmcnt(10)
	s_barrier
	s_setprio 1
	v_mfma_f32_16x16x32_bf16 v[44:47], v[196:199], v[162:165], v[44:47]
	v_mfma_f32_16x16x32_bf16 v[40:43], v[204:207], v[162:165], v[40:43]
	v_mfma_f32_16x16x32_bf16 v[28:31], v[196:199], v[172:175], v[28:31]
	v_mfma_f32_16x16x32_bf16 v[24:27], v[204:207], v[172:175], v[24:27]
	v_mfma_f32_16x16x32_bf16 v[12:15], v[196:199], v[180:183], v[12:15]
	v_mfma_f32_16x16x32_bf16 v[8:11], v[204:207], v[180:183], v[8:11]
	v_mfma_f32_16x16x32_bf16 v[4:7], v[196:199], v[188:191], v[4:7]
	v_mfma_f32_16x16x32_bf16 v[0:3], v[204:207], v[188:191], v[0:3]
	v_mfma_f32_16x16x32_bf16 v[44:47], v[200:203], v[166:169], v[44:47]
	v_mfma_f32_16x16x32_bf16 v[40:43], v[208:211], v[166:169], v[40:43]
	v_mfma_f32_16x16x32_bf16 v[28:31], v[200:203], v[176:179], v[28:31]
	v_mfma_f32_16x16x32_bf16 v[24:27], v[208:211], v[176:179], v[24:27]
	v_mfma_f32_16x16x32_bf16 v[12:15], v[200:203], v[184:187], v[12:15]
	v_mfma_f32_16x16x32_bf16 v[8:11], v[208:211], v[184:187], v[8:11]
	v_mfma_f32_16x16x32_bf16 v[4:7], v[200:203], v[192:195], v[4:7]
	v_mfma_f32_16x16x32_bf16 v[0:3], v[208:211], v[192:195], v[0:3]
	s_setprio 0
	s_add_i32 s46, s46, 2
	s_add_u32 s20, s20, 0x100
	s_addc_u32 s21, s21, 0
	s_add_u32 s44, s44, 0x100
	s_addc_u32 s45, s45, 0
	s_cmp_gt_u32 s46, 29
	s_barrier
	s_cbranch_scc0 .LBB0_578
	v_lshl_add_u32 v146, s10, 8, v140
	v_lshl_or_b32 v148, s41, 8, v142
	v_ashrrev_i32_e32 v147, 31, v146
	v_ashrrev_i32_e32 v149, 31, v148
	v_lshlrev_b64 v[150:151], 12, v[146:147]
	v_lshl_add_u64 v[150:151], s[2:3], 0, v[150:151]
	v_lshlrev_b64 v[148:149], 1, v[148:149]
	v_lshl_add_u64 v[150:151], v[150:151], 0, v[148:149]
	s_mov_b32 s10, 0x80000
	s_mov_b64 s[20:21], 0x80000
	v_cvt_pk_bf16_f32 v60, v60, v61
	v_cvt_pk_bf16_f32 v61, v62, v63
	v_cvt_pk_bf16_f32 v62, v56, v57
	v_add_co_u32_e32 v56, vcc, s10, v150
	v_cvt_pk_bf16_f32 v68, v68, v69
	v_cvt_pk_bf16_f32 v69, v70, v71
	v_cvt_pk_bf16_f32 v70, v64, v65
	v_lshl_add_u64 v[64:65], v[150:151], 0, s[20:21]
	v_addc_co_u32_e32 v57, vcc, 0, v151, vcc
	v_cvt_pk_bf16_f32 v44, v44, v45
	v_cvt_pk_bf16_f32 v45, v46, v47
	v_cvt_pk_bf16_f32 v46, v40, v41
	v_cvt_pk_bf16_f32 v47, v42, v43
	s_mov_b32 s10, 0x90000
	v_cvt_pk_bf16_f32 v108, v108, v109
	v_cvt_pk_bf16_f32 v109, v110, v111
	v_cvt_pk_bf16_f32 v110, v104, v105
	v_or_b32_e32 v104, 16, v146
	global_store_dwordx4 v[64:65], v[44:47], off offset:256
	s_mov_b64 s[20:21], 0x90000
	v_ashrrev_i32_e32 v105, 31, v104
	v_add_co_u32_e32 v46, vcc, s10, v150
	v_cvt_pk_bf16_f32 v92, v92, v93
	v_cvt_pk_bf16_f32 v93, v94, v95
	v_cvt_pk_bf16_f32 v94, v88, v89
	v_or_b32_e32 v88, 32, v146
	v_lshl_add_u64 v[44:45], v[150:151], 0, s[20:21]
	v_addc_co_u32_e32 v47, vcc, 0, v151, vcc
	v_cvt_pk_bf16_f32 v28, v28, v29
	v_cvt_pk_bf16_f32 v29, v30, v31
	v_cvt_pk_bf16_f32 v30, v24, v25
	v_cvt_pk_bf16_f32 v31, v26, v27
	s_mov_b32 s10, 0xa0000
	v_lshlrev_b64 v[104:105], 12, v[104:105]
	v_ashrrev_i32_e32 v89, 31, v88
	v_cvt_pk_bf16_f32 v76, v76, v77
	v_cvt_pk_bf16_f32 v77, v78, v79
	v_cvt_pk_bf16_f32 v78, v72, v73
	v_or_b32_e32 v72, 48, v146
	global_store_dwordx4 v[44:45], v[28:31], off offset:256
	s_mov_b64 s[20:21], 0xa0000
	v_cvt_pk_bf16_f32 v111, v106, v107
	v_add_co_u32_e32 v30, vcc, s10, v150
	v_lshl_add_u64 v[104:105], s[2:3], 0, v[104:105]
	v_lshlrev_b64 v[88:89], 12, v[88:89]
	v_ashrrev_i32_e32 v73, 31, v72
	v_lshl_add_u64 v[28:29], v[150:151], 0, s[20:21]
	v_addc_co_u32_e32 v31, vcc, 0, v151, vcc
	v_cvt_pk_bf16_f32 v12, v12, v13
	v_cvt_pk_bf16_f32 v13, v14, v15
	v_cvt_pk_bf16_f32 v14, v8, v9
	v_cvt_pk_bf16_f32 v15, v10, v11
	global_store_dwordx4 v[150:151], v[108:111], off offset:256
	v_cvt_pk_bf16_f32 v95, v90, v91
	v_lshl_add_u64 v[88:89], s[2:3], 0, v[88:89]
	v_lshl_add_u64 v[108:109], v[104:105], 0, v[148:149]
	v_lshlrev_b64 v[72:73], 12, v[72:73]
	global_store_dwordx4 v[28:29], v[12:15], off offset:256
	global_store_dwordx4 v[108:109], v[92:95], off offset:256
	v_cvt_pk_bf16_f32 v79, v74, v75
	v_add_co_u32_e32 v14, vcc, 0xb0000, v150
	v_lshl_add_u64 v[92:93], v[88:89], 0, v[148:149]
	v_lshl_add_u64 v[72:73], s[2:3], 0, v[72:73]
	s_mov_b64 s[20:21], 0xb0000
	v_addc_co_u32_e32 v15, vcc, 0, v151, vcc
	v_cvt_pk_bf16_f32 v124, v124, v125
	v_cvt_pk_bf16_f32 v125, v126, v127
	v_cvt_pk_bf16_f32 v126, v120, v121
	v_cvt_pk_bf16_f32 v127, v122, v123
	v_cvt_pk_bf16_f32 v104, v116, v117
	v_cvt_pk_bf16_f32 v105, v118, v119
	v_cvt_pk_bf16_f32 v106, v112, v113
	v_cvt_pk_bf16_f32 v107, v114, v115
	v_cvt_pk_bf16_f32 v88, v100, v101
	v_cvt_pk_bf16_f32 v89, v102, v103
	v_cvt_pk_bf16_f32 v90, v96, v97
	v_cvt_pk_bf16_f32 v91, v98, v99
	global_store_dwordx4 v[92:93], v[76:79], off offset:256
	v_cvt_pk_bf16_f32 v74, v80, v81
	v_cvt_pk_bf16_f32 v75, v82, v83
	v_lshl_add_u64 v[76:77], v[72:73], 0, v[148:149]
	v_cvt_pk_bf16_f32 v72, v84, v85
	v_cvt_pk_bf16_f32 v73, v86, v87
	v_cvt_pk_bf16_f32 v71, v66, v67
	v_cvt_pk_bf16_f32 v63, v58, v59
	v_cvt_pk_bf16_f32 v40, v52, v53
	v_cvt_pk_bf16_f32 v41, v54, v55
	v_cvt_pk_bf16_f32 v42, v48, v49
	v_cvt_pk_bf16_f32 v43, v50, v51
	v_cvt_pk_bf16_f32 v24, v36, v37
	v_cvt_pk_bf16_f32 v25, v38, v39
	v_cvt_pk_bf16_f32 v26, v32, v33
	v_cvt_pk_bf16_f32 v27, v34, v35
	v_lshl_add_u64 v[12:13], v[150:151], 0, s[20:21]
	v_cvt_pk_bf16_f32 v8, v20, v21
	v_cvt_pk_bf16_f32 v9, v22, v23
	v_cvt_pk_bf16_f32 v10, v16, v17
	v_cvt_pk_bf16_f32 v11, v18, v19
	v_cvt_pk_bf16_f32 v4, v4, v5
	v_cvt_pk_bf16_f32 v5, v6, v7
	v_cvt_pk_bf16_f32 v6, v0, v1
	v_cvt_pk_bf16_f32 v7, v2, v3
	s_and_b64 vcc, exec, s[8:9]
	s_mov_b32 s41, s14
	s_mov_b32 s10, s12
	s_mov_b64 s[22:23], s[18:19]
	s_mov_b64 s[20:21], s[16:17]
	global_store_dwordx4 v[150:151], v[124:127], off
	global_store_dwordx4 v[108:109], v[104:107], off
	global_store_dwordx4 v[92:93], v[88:91], off
	global_store_dwordx4 v[76:77], v[72:75], off
	global_store_dwordx4 v[76:77], v[68:71], off offset:256
	global_store_dwordx4 v[56:57], v[60:63], off
	global_store_dwordx4 v[46:47], v[40:43], off
	global_store_dwordx4 v[30:31], v[24:27], off
	global_store_dwordx4 v[14:15], v[8:11], off
	global_store_dwordx4 v[12:13], v[4:7], off offset:256
	s_cbranch_vccz .LBB0_571
	s_waitcnt vmcnt(0)
	s_cmpk_gt_u32 s27, 0xff
	s_cbranch_scc1 .LBB0_582
	s_barrier
